# P2 MY_t conv pass rewritten: branch-free, all Kt/D loads of an item issued together (1 round trip per item instead of ~24 serialized conditional loads), same f32 add order
# speedup vs baseline: 1.0121x; 1.0121x over previous
; #define GAS __attribute__((address_space(1)))
; __global__ void __launch_bounds__(512, 2) fwd_mega(Args a) {
;     ...
;           for (int idx = gtid; idx < 32 * 256 * 32; idx += NTH) {
;               const int k8 = idx & 31, o = (idx >> 5) & 255, g = idx >> 13, j = o >> 4, p = o & 15, j2 = k8 >> 1, q0 = (k8 & 1) * 8;
;               float v[8];
; #pragma unroll
;               for (int q = 0; q < 8; ++q) { const int p2 = q0 + q; float x = 0.f;
;                   if (j2 <= j) x += Kt[((size_t)(g * 16 + (j - j2))) * 256 + p * 16 + p2];
;                   if (j2 >= j) x += Kt[((size_t)((32 + g) * 16 + (j2 - j))) * 256 + p * 16 + p2];
;                   if (j2 == j && p2 == p) x += dsk[g * 16 + p];
;                   v[q] = x; }
;               u32x4 w; w.x = pk2(v[0], v[1]); w.y = pk2(v[2], v[3]); w.z = pk2(v[4], v[5]); w.w = pk2(v[6], v[7]);
;               *(GAS u32x4*)(MY_t + ((size_t)(g * 256 + o) * 512 + k8 * 8)) = w;
;           } }
.LBB0_559:
	v_bfe_u32 v10, v12, 9, 4
	v_ashrrev_i32_e32 v15, 13, v12
	v_bfe_u32 v16, v12, 5, 4
	v_and_b32_e32 v17, 8, v14
	v_sub_u32_e32 v4, v10, v13
	v_sub_u32_e32 v6, v13, v10
	v_cmp_le_i32_e64 s[40:41], 0, v4
	v_cmp_le_i32_e64 s[42:43], 0, v6
	v_cmp_eq_u32_e64 s[4:5], v10, v13
	v_and_b32_e32 v5, 15, v4
	v_and_b32_e32 v6, 15, v6
	v_lshl_or_b32 v5, v15, 4, v5
	v_lshl_or_b32 v6, v15, 4, v6
	v_add_u32_e32 v6, 0x200, v6
	v_lshlrev_b32_e32 v7, 6, v16
	v_lshl_or_b32 v7, v17, 2, v7
	v_lshl_add_u32 v5, v5, 10, v7
	v_lshl_add_u32 v6, v6, 10, v7
	v_lshl_or_b32 v8, v15, 4, v16
	v_lshlrev_b32_e32 v8, 2, v8
	v_sub_u32_e32 v9, v16, v17
	s_waitcnt lgkmcnt(0)
	global_load_dwordx4 v[20:23], v5, s[36:37]
	global_load_dwordx4 v[24:27], v5, s[36:37] offset:16
	global_load_dwordx4 v[28:31], v6, s[36:37]
	global_load_dwordx4 v[32:35], v6, s[36:37] offset:16
	global_load_dword v36, v8, s[8:9]
	s_waitcnt vmcnt(0)
	v_add_f32_e32 v40, 0, v20
	v_cmp_eq_u32_e32 vcc, 0, v9
	v_cndmask_b32_e64 v40, 0, v40, s[40:41]
	s_and_b64 vcc, vcc, s[4:5]
	v_add_f32_e32 v37, v40, v28
	v_cndmask_b32_e64 v40, v40, v37, s[42:43]
	v_add_f32_e32 v37, v40, v36
	v_cndmask_b32_e32 v40, v40, v37, vcc
	v_add_f32_e32 v41, 0, v21
	v_cmp_eq_u32_e32 vcc, 1, v9
	v_cndmask_b32_e64 v41, 0, v41, s[40:41]
	s_and_b64 vcc, vcc, s[4:5]
	v_add_f32_e32 v37, v41, v29
	v_cndmask_b32_e64 v41, v41, v37, s[42:43]
	v_add_f32_e32 v37, v41, v36
	v_cndmask_b32_e32 v41, v41, v37, vcc
	v_add_f32_e32 v42, 0, v22
	v_cmp_eq_u32_e32 vcc, 2, v9
	v_cndmask_b32_e64 v42, 0, v42, s[40:41]
	s_and_b64 vcc, vcc, s[4:5]
	v_add_f32_e32 v37, v42, v30
	v_cndmask_b32_e64 v42, v42, v37, s[42:43]
	v_add_f32_e32 v37, v42, v36
	v_cndmask_b32_e32 v42, v42, v37, vcc
	v_add_f32_e32 v43, 0, v23
	v_cmp_eq_u32_e32 vcc, 3, v9
	v_cndmask_b32_e64 v43, 0, v43, s[40:41]
	s_and_b64 vcc, vcc, s[4:5]
	v_add_f32_e32 v37, v43, v31
	v_cndmask_b32_e64 v43, v43, v37, s[42:43]
	v_add_f32_e32 v37, v43, v36
	v_cndmask_b32_e32 v43, v43, v37, vcc
	v_add_f32_e32 v44, 0, v24
	v_cmp_eq_u32_e32 vcc, 4, v9
	v_cndmask_b32_e64 v44, 0, v44, s[40:41]
	s_and_b64 vcc, vcc, s[4:5]
	v_add_f32_e32 v37, v44, v32
	v_cndmask_b32_e64 v44, v44, v37, s[42:43]
	v_add_f32_e32 v37, v44, v36
	v_cndmask_b32_e32 v44, v44, v37, vcc
	v_add_f32_e32 v45, 0, v25
	v_cmp_eq_u32_e32 vcc, 5, v9
	v_cndmask_b32_e64 v45, 0, v45, s[40:41]
	s_and_b64 vcc, vcc, s[4:5]
	v_add_f32_e32 v37, v45, v33
	v_cndmask_b32_e64 v45, v45, v37, s[42:43]
	v_add_f32_e32 v37, v45, v36
	v_cndmask_b32_e32 v45, v45, v37, vcc
	v_add_f32_e32 v46, 0, v26
	v_cmp_eq_u32_e32 vcc, 6, v9
	v_cndmask_b32_e64 v46, 0, v46, s[40:41]
	s_and_b64 vcc, vcc, s[4:5]
	v_add_f32_e32 v37, v46, v34
	v_cndmask_b32_e64 v46, v46, v37, s[42:43]
	v_add_f32_e32 v37, v46, v36
	v_cndmask_b32_e32 v46, v46, v37, vcc
	v_add_f32_e32 v47, 0, v27
	v_cmp_eq_u32_e32 vcc, 7, v9
	v_cndmask_b32_e64 v47, 0, v47, s[40:41]
	s_and_b64 vcc, vcc, s[4:5]
	v_add_f32_e32 v37, v47, v35
	v_cndmask_b32_e64 v47, v47, v37, s[42:43]
	v_add_f32_e32 v37, v47, v36
	v_cndmask_b32_e32 v47, v47, v37, vcc
	v_bfe_u32 v8, v12, 5, 8
	v_lshl_or_b32 v8, v15, 8, v8
	v_ashrrev_i32_e32 v9, 31, v8
	v_lshlrev_b64 v[8:9], 10, v[8:9]
	v_lshl_add_u64 v[8:9], v[2:3], 0, v[8:9]
	v_add_u32_e32 v12, s28, v12
	v_cmp_lt_i32_e32 vcc, s11, v12
	v_cvt_pk_bf16_f32 v4, v40, v41
	v_cvt_pk_bf16_f32 v5, v42, v43
	v_cvt_pk_bf16_f32 v6, v44, v45
	v_cvt_pk_bf16_f32 v7, v46, v47
	s_or_b64 s[38:39], vcc, s[38:39]
	v_add_u32_e32 v14, s3, v14
	global_store_dwordx4 v[8:9], v[4:7], off
	s_andn2_b64 exec, exec, s[38:39]
	s_cbranch_execnz .LBB0_559
